# E49: E48 plus conv y-parking converts pairs with v_cvt_pk_bf16_f32 (RNE, same as the bit trick) and writes lo/hi halves - 192 fewer VALU ops per wave on the conv tail
# baseline (speedup 1.0000x reference)
.LBB0_2178:
	s_waitcnt lgkmcnt(0)
	s_and_b64 vcc, exec, s[4:5]
	s_barrier
	s_cbranch_vccnz .LBB0_2180
	v_div_scale_f32 v203, s[4:5], v200, v200, 1.0
	v_rcp_f32_e32 v204, v203
	v_div_scale_f32 v205, vcc, 1.0, v200, 1.0
	v_lshl_add_u32 v160, v160, 13, s39
	v_fma_f32 v206, -v203, v204, 1.0
	v_fmac_f32_e32 v204, v206, v204
	v_mul_f32_e32 v206, v205, v204
	v_fma_f32 v207, -v203, v206, v205
	v_fmac_f32_e32 v206, v207, v204
	v_fma_f32 v203, -v203, v206, v205
	v_div_fmas_f32 v203, v203, v204, v206
	v_div_fixup_f32 v200, v203, v200, 1.0
	v_add3_u32 v160, v160, v201, v202
	v_mul_f32_e32 v0, v200, v0
	v_mul_f32_e32 v1, v200, v1
	v_cvt_pk_bf16_f32 v0, v0, v1
	ds_write_b16 v160, v0
	ds_write_b16_d16_hi v160, v0 offset:32
	v_mul_f32_e32 v0, v200, v2
	v_mul_f32_e32 v1, v200, v3
	v_cvt_pk_bf16_f32 v0, v0, v1
	ds_write_b16 v160, v0 offset:64
	ds_write_b16_d16_hi v160, v0 offset:96
	v_mul_f32_e32 v0, v200, v4
	v_mul_f32_e32 v1, v200, v5
	v_cvt_pk_bf16_f32 v0, v0, v1
	ds_write_b16 v160, v0 offset:256
	ds_write_b16_d16_hi v160, v0 offset:288
	v_mul_f32_e32 v0, v200, v6
	v_mul_f32_e32 v1, v200, v7
	v_cvt_pk_bf16_f32 v0, v0, v1
	ds_write_b16 v160, v0 offset:320
	ds_write_b16_d16_hi v160, v0 offset:352
	v_mul_f32_e32 v0, v200, v8
	v_mul_f32_e32 v1, v200, v9
	v_cvt_pk_bf16_f32 v0, v0, v1
	ds_write_b16 v160, v0 offset:512
	ds_write_b16_d16_hi v160, v0 offset:544
	v_mul_f32_e32 v0, v200, v10
	v_mul_f32_e32 v1, v200, v11
	v_cvt_pk_bf16_f32 v0, v0, v1
	ds_write_b16 v160, v0 offset:576
	ds_write_b16_d16_hi v160, v0 offset:608
	v_mul_f32_e32 v0, v200, v12
	v_mul_f32_e32 v1, v200, v13
	v_cvt_pk_bf16_f32 v0, v0, v1
	ds_write_b16 v160, v0 offset:768
	ds_write_b16_d16_hi v160, v0 offset:800
	v_mul_f32_e32 v0, v200, v14
	v_mul_f32_e32 v1, v200, v15
	v_cvt_pk_bf16_f32 v0, v0, v1
	ds_write_b16 v160, v0 offset:832
	ds_write_b16_d16_hi v160, v0 offset:864
	v_mul_f32_e32 v0, v200, v16
	v_mul_f32_e32 v1, v200, v17
	v_cvt_pk_bf16_f32 v0, v0, v1
	ds_write_b16 v160, v0 offset:1024
	ds_write_b16_d16_hi v160, v0 offset:1056
	v_mul_f32_e32 v0, v200, v18
	v_mul_f32_e32 v1, v200, v19
	v_cvt_pk_bf16_f32 v0, v0, v1
	ds_write_b16 v160, v0 offset:1088
	ds_write_b16_d16_hi v160, v0 offset:1120
	v_mul_f32_e32 v0, v200, v20
	v_mul_f32_e32 v1, v200, v21
	v_cvt_pk_bf16_f32 v0, v0, v1
	ds_write_b16 v160, v0 offset:1280
	ds_write_b16_d16_hi v160, v0 offset:1312
	v_mul_f32_e32 v0, v200, v22
	v_mul_f32_e32 v1, v200, v23
	v_cvt_pk_bf16_f32 v0, v0, v1
	ds_write_b16 v160, v0 offset:1344
	ds_write_b16_d16_hi v160, v0 offset:1376
	v_mul_f32_e32 v0, v200, v24
	v_mul_f32_e32 v1, v200, v25
	v_cvt_pk_bf16_f32 v0, v0, v1
	ds_write_b16 v160, v0 offset:1536
	ds_write_b16_d16_hi v160, v0 offset:1568
	v_mul_f32_e32 v0, v200, v26
	v_mul_f32_e32 v1, v200, v27
	v_cvt_pk_bf16_f32 v0, v0, v1
	ds_write_b16 v160, v0 offset:1600
	ds_write_b16_d16_hi v160, v0 offset:1632
	v_mul_f32_e32 v0, v200, v28
	v_mul_f32_e32 v1, v200, v29
	v_cvt_pk_bf16_f32 v0, v0, v1
	ds_write_b16 v160, v0 offset:1792
	ds_write_b16_d16_hi v160, v0 offset:1824
	v_mul_f32_e32 v0, v200, v30
	v_mul_f32_e32 v1, v200, v31
	v_cvt_pk_bf16_f32 v0, v0, v1
	ds_write_b16 v160, v0 offset:1856
	ds_write_b16_d16_hi v160, v0 offset:1888
	v_mul_f32_e32 v0, v200, v32
	v_mul_f32_e32 v1, v200, v33
	v_cvt_pk_bf16_f32 v0, v0, v1
	ds_write_b16 v160, v0 offset:2048
	ds_write_b16_d16_hi v160, v0 offset:2080
	v_mul_f32_e32 v0, v200, v34
	v_mul_f32_e32 v1, v200, v35
	v_cvt_pk_bf16_f32 v0, v0, v1
	ds_write_b16 v160, v0 offset:2112
	ds_write_b16_d16_hi v160, v0 offset:2144
	v_mul_f32_e32 v0, v200, v36
	v_mul_f32_e32 v1, v200, v37
	v_cvt_pk_bf16_f32 v0, v0, v1
	ds_write_b16 v160, v0 offset:2304
	ds_write_b16_d16_hi v160, v0 offset:2336
	v_mul_f32_e32 v0, v200, v38
	v_mul_f32_e32 v1, v200, v39
	v_cvt_pk_bf16_f32 v0, v0, v1
	ds_write_b16 v160, v0 offset:2368
	ds_write_b16_d16_hi v160, v0 offset:2400
	v_mul_f32_e32 v0, v200, v40
	v_mul_f32_e32 v1, v200, v41
	v_cvt_pk_bf16_f32 v0, v0, v1
	ds_write_b16 v160, v0 offset:2560
	ds_write_b16_d16_hi v160, v0 offset:2592
	v_mul_f32_e32 v0, v200, v42
	v_mul_f32_e32 v1, v200, v43
	v_cvt_pk_bf16_f32 v0, v0, v1
	ds_write_b16 v160, v0 offset:2624
	ds_write_b16_d16_hi v160, v0 offset:2656
	v_mul_f32_e32 v0, v200, v44
	v_mul_f32_e32 v1, v200, v45
	v_cvt_pk_bf16_f32 v0, v0, v1
	ds_write_b16 v160, v0 offset:2816
	ds_write_b16_d16_hi v160, v0 offset:2848
	v_mul_f32_e32 v0, v200, v46
	v_mul_f32_e32 v1, v200, v47
	v_cvt_pk_bf16_f32 v0, v0, v1
	ds_write_b16 v160, v0 offset:2880
	ds_write_b16_d16_hi v160, v0 offset:2912
	v_mul_f32_e32 v0, v200, v48
	v_mul_f32_e32 v1, v200, v49
	v_cvt_pk_bf16_f32 v0, v0, v1
	ds_write_b16 v160, v0 offset:3072
	ds_write_b16_d16_hi v160, v0 offset:3104
	v_mul_f32_e32 v0, v200, v50
	v_mul_f32_e32 v1, v200, v51
	v_cvt_pk_bf16_f32 v0, v0, v1
	ds_write_b16 v160, v0 offset:3136
	ds_write_b16_d16_hi v160, v0 offset:3168
	v_mul_f32_e32 v0, v200, v52
	v_mul_f32_e32 v1, v200, v53
	v_cvt_pk_bf16_f32 v0, v0, v1
	ds_write_b16 v160, v0 offset:3328
	ds_write_b16_d16_hi v160, v0 offset:3360
	v_mul_f32_e32 v0, v200, v54
	v_mul_f32_e32 v1, v200, v55
	v_cvt_pk_bf16_f32 v0, v0, v1
	ds_write_b16 v160, v0 offset:3392
	ds_write_b16_d16_hi v160, v0 offset:3424
	v_mul_f32_e32 v0, v200, v56
	v_mul_f32_e32 v1, v200, v57
	v_cvt_pk_bf16_f32 v0, v0, v1
	ds_write_b16 v160, v0 offset:3584
	ds_write_b16_d16_hi v160, v0 offset:3616
	v_mul_f32_e32 v0, v200, v58
	v_mul_f32_e32 v1, v200, v59
	v_cvt_pk_bf16_f32 v0, v0, v1
	ds_write_b16 v160, v0 offset:3648
	ds_write_b16_d16_hi v160, v0 offset:3680
	v_mul_f32_e32 v0, v200, v60
	v_mul_f32_e32 v1, v200, v61
	v_cvt_pk_bf16_f32 v0, v0, v1
	ds_write_b16 v160, v0 offset:3840
	ds_write_b16_d16_hi v160, v0 offset:3872
	v_mul_f32_e32 v0, v200, v62
	v_mul_f32_e32 v1, v200, v63
	v_cvt_pk_bf16_f32 v0, v0, v1
	ds_write_b16 v160, v0 offset:3904
	ds_write_b16_d16_hi v160, v0 offset:3936
	v_mul_f32_e32 v0, v200, v64
	v_mul_f32_e32 v1, v200, v65
	v_cvt_pk_bf16_f32 v0, v0, v1
	ds_write_b16 v160, v0 offset:4096
	ds_write_b16_d16_hi v160, v0 offset:4128
	v_mul_f32_e32 v0, v200, v66
	v_mul_f32_e32 v1, v200, v67
	v_cvt_pk_bf16_f32 v0, v0, v1
	ds_write_b16 v160, v0 offset:4160
	ds_write_b16_d16_hi v160, v0 offset:4192
	v_mul_f32_e32 v0, v200, v68
	v_mul_f32_e32 v1, v200, v69
	v_cvt_pk_bf16_f32 v0, v0, v1
	ds_write_b16 v160, v0 offset:4352
	ds_write_b16_d16_hi v160, v0 offset:4384
	v_mul_f32_e32 v0, v200, v70
	v_mul_f32_e32 v1, v200, v71
	v_cvt_pk_bf16_f32 v0, v0, v1
	ds_write_b16 v160, v0 offset:4416
	ds_write_b16_d16_hi v160, v0 offset:4448
	v_mul_f32_e32 v0, v200, v72
	v_mul_f32_e32 v1, v200, v73
	v_cvt_pk_bf16_f32 v0, v0, v1
	ds_write_b16 v160, v0 offset:4608
	ds_write_b16_d16_hi v160, v0 offset:4640
	v_mul_f32_e32 v0, v200, v74
	v_mul_f32_e32 v1, v200, v75
	v_cvt_pk_bf16_f32 v0, v0, v1
	ds_write_b16 v160, v0 offset:4672
	ds_write_b16_d16_hi v160, v0 offset:4704
	v_mul_f32_e32 v0, v200, v76
	v_mul_f32_e32 v1, v200, v77
	v_cvt_pk_bf16_f32 v0, v0, v1
	ds_write_b16 v160, v0 offset:4864
	ds_write_b16_d16_hi v160, v0 offset:4896
	v_mul_f32_e32 v0, v200, v78
	v_mul_f32_e32 v1, v200, v79
	v_cvt_pk_bf16_f32 v0, v0, v1
	ds_write_b16 v160, v0 offset:4928
	ds_write_b16_d16_hi v160, v0 offset:4960
	v_mul_f32_e32 v0, v200, v80
	v_mul_f32_e32 v1, v200, v81
	v_cvt_pk_bf16_f32 v0, v0, v1
	ds_write_b16 v160, v0 offset:5120
	ds_write_b16_d16_hi v160, v0 offset:5152
	v_mul_f32_e32 v0, v200, v82
	v_mul_f32_e32 v1, v200, v83
	v_cvt_pk_bf16_f32 v0, v0, v1
	ds_write_b16 v160, v0 offset:5184
	ds_write_b16_d16_hi v160, v0 offset:5216
	v_mul_f32_e32 v0, v200, v84
	v_mul_f32_e32 v1, v200, v85
	v_cvt_pk_bf16_f32 v0, v0, v1
	ds_write_b16 v160, v0 offset:5376
	ds_write_b16_d16_hi v160, v0 offset:5408
	v_mul_f32_e32 v0, v200, v86
	v_mul_f32_e32 v1, v200, v87
	v_cvt_pk_bf16_f32 v0, v0, v1
	ds_write_b16 v160, v0 offset:5440
	ds_write_b16_d16_hi v160, v0 offset:5472
	v_mul_f32_e32 v0, v200, v88
	v_mul_f32_e32 v1, v200, v89
	v_cvt_pk_bf16_f32 v0, v0, v1
	ds_write_b16 v160, v0 offset:5632
	ds_write_b16_d16_hi v160, v0 offset:5664
	v_mul_f32_e32 v0, v200, v90
	v_mul_f32_e32 v1, v200, v91
	v_cvt_pk_bf16_f32 v0, v0, v1
	ds_write_b16 v160, v0 offset:5696
	ds_write_b16_d16_hi v160, v0 offset:5728
	v_mul_f32_e32 v0, v200, v92
	v_mul_f32_e32 v1, v200, v93
	v_cvt_pk_bf16_f32 v0, v0, v1
	ds_write_b16 v160, v0 offset:5888
	ds_write_b16_d16_hi v160, v0 offset:5920
	v_mul_f32_e32 v0, v200, v94
	v_mul_f32_e32 v1, v200, v95
	v_cvt_pk_bf16_f32 v0, v0, v1
	ds_write_b16 v160, v0 offset:5952
	ds_write_b16_d16_hi v160, v0 offset:5984
	v_mul_f32_e32 v0, v200, v96
	v_mul_f32_e32 v1, v200, v97
	v_cvt_pk_bf16_f32 v0, v0, v1
	ds_write_b16 v160, v0 offset:6144
	ds_write_b16_d16_hi v160, v0 offset:6176
	v_mul_f32_e32 v0, v200, v98
	v_mul_f32_e32 v1, v200, v99
	v_cvt_pk_bf16_f32 v0, v0, v1
	ds_write_b16 v160, v0 offset:6208
	ds_write_b16_d16_hi v160, v0 offset:6240
	v_mul_f32_e32 v0, v200, v100
	v_mul_f32_e32 v1, v200, v101
	v_cvt_pk_bf16_f32 v0, v0, v1
	ds_write_b16 v160, v0 offset:6400
	ds_write_b16_d16_hi v160, v0 offset:6432
	v_mul_f32_e32 v0, v200, v102
	v_mul_f32_e32 v1, v200, v103
	v_cvt_pk_bf16_f32 v0, v0, v1
	ds_write_b16 v160, v0 offset:6464
	ds_write_b16_d16_hi v160, v0 offset:6496
	v_mul_f32_e32 v0, v200, v104
	v_mul_f32_e32 v1, v200, v105
	v_cvt_pk_bf16_f32 v0, v0, v1
	ds_write_b16 v160, v0 offset:6656
	ds_write_b16_d16_hi v160, v0 offset:6688
	v_mul_f32_e32 v0, v200, v106
	v_mul_f32_e32 v1, v200, v107
	v_cvt_pk_bf16_f32 v0, v0, v1
	ds_write_b16 v160, v0 offset:6720
	ds_write_b16_d16_hi v160, v0 offset:6752
	v_mul_f32_e32 v0, v200, v108
	v_mul_f32_e32 v1, v200, v109
	v_cvt_pk_bf16_f32 v0, v0, v1
	ds_write_b16 v160, v0 offset:6912
	ds_write_b16_d16_hi v160, v0 offset:6944
	v_mul_f32_e32 v0, v200, v110
	v_mul_f32_e32 v1, v200, v111
	v_cvt_pk_bf16_f32 v0, v0, v1
	ds_write_b16 v160, v0 offset:6976
	ds_write_b16_d16_hi v160, v0 offset:7008
	v_mul_f32_e32 v0, v200, v112
	v_mul_f32_e32 v1, v200, v113
	v_cvt_pk_bf16_f32 v0, v0, v1
	ds_write_b16 v160, v0 offset:7168
	ds_write_b16_d16_hi v160, v0 offset:7200
	v_mul_f32_e32 v0, v200, v114
	v_mul_f32_e32 v1, v200, v115
	v_cvt_pk_bf16_f32 v0, v0, v1
	ds_write_b16 v160, v0 offset:7232
	ds_write_b16_d16_hi v160, v0 offset:7264
	v_mul_f32_e32 v0, v200, v116
	v_mul_f32_e32 v1, v200, v117
	v_cvt_pk_bf16_f32 v0, v0, v1
	ds_write_b16 v160, v0 offset:7424
	ds_write_b16_d16_hi v160, v0 offset:7456
	v_mul_f32_e32 v0, v200, v118
	v_mul_f32_e32 v1, v200, v119
	v_cvt_pk_bf16_f32 v0, v0, v1
	ds_write_b16 v160, v0 offset:7488
	ds_write_b16_d16_hi v160, v0 offset:7520
	v_mul_f32_e32 v0, v200, v120
	v_mul_f32_e32 v1, v200, v121
	v_cvt_pk_bf16_f32 v0, v0, v1
	ds_write_b16 v160, v0 offset:7680
	ds_write_b16_d16_hi v160, v0 offset:7712
	v_mul_f32_e32 v0, v200, v122
	v_mul_f32_e32 v1, v200, v123
	v_cvt_pk_bf16_f32 v0, v0, v1
	ds_write_b16 v160, v0 offset:7744
	ds_write_b16_d16_hi v160, v0 offset:7776
	v_mul_f32_e32 v0, v200, v124
	v_mul_f32_e32 v1, v200, v125
	v_cvt_pk_bf16_f32 v0, v0, v1
	ds_write_b16 v160, v0 offset:7936
	ds_write_b16_d16_hi v160, v0 offset:7968
	v_mul_f32_e32 v0, v200, v126
	v_mul_f32_e32 v1, v200, v127
	v_cvt_pk_bf16_f32 v0, v0, v1
	ds_write_b16 v160, v0 offset:8000
	ds_write_b16_d16_hi v160, v0 offset:8032
